# baseline (speedup 1.0000x reference)
; __device__ __forceinline__ void transpose_tile(const int tid_, const float* __restrict__ src, const float* __restrict__ gain, int N, int K, u16* __restrict__ dst, int kt, int nt, int snt, float* lds) {
;   const int t = tid_, kr = t >> 3, nc = (t & 7) * 8;
;   f32x4 a = {0, 0, 0, 0}, b = {0, 0, 0, 0};
;   if (snt * 64 < N) {
;     const float* s = src + (size_t)(kt * 64 + kr) * N + snt * 64 + nc;
;     a = *reinterpret_cast<const f32x4*>(s); b = *reinterpret_cast<const f32x4*>(s + 4);
;     if (gain) { const float g = gain[kt * 64 + kr]; a = a * g; b = b * g; }
;   }
;   float* l = lds + kr * 65 + nc;
;   l[0] = a[0]; l[1] = a[1]; l[2] = a[2]; l[3] = a[3]; l[4] = b[0]; l[5] = b[1]; l[6] = b[2]; l[7] = b[3];
;   __syncthreads();
;   const int n = t >> 3, k0 = (t & 7) * 8;
;   float f[8];
; #pragma unroll
;   for (int i = 0; i < 8; ++i) f[i] = lds[(k0 + i) * 65 + n];
;   *reinterpret_cast<u32x4*>(dst + (size_t)(nt * 64 + n) * K + kt * 64 + k0) = pack8(f);
;   __syncthreads();
; }
; __device__ __forceinline__ void phase_prep(const int tid_, CP p, float* lds) {
;     ...
;   for (int id = blockIdx.x; id < 20032; id += gridDim.x) {
;     int r = id; const float* src; const float* gain = nullptr; u16* dst; int N, Np, K;
;     if (r < 2048) { src = p->w_in0; gain = p->norm_mix0; dst = (u16*)(ws + OFF_WIN); N = NIN; Np = NINP; K = DM; }
;     else if ((r -= 2048) < 192) { src = p->w_qb; gain = p->q_a_norm; dst = (u16*)(ws + OFF_WQB); N = NQ; Np = NQ; K = QR; }
;     else if ((r -= 192) < 128) { src = p->w_kvb; gain = p->kv_a_norm; dst = (u16*)(ws + OFF_WKVB); N = NKV; Np = NKV; K = KVR; }
;     else if ((r -= 128) < 1024) { src = p->w_o0; dst = (u16*)(ws + OFF_WO); N = DM; Np = DM; K = DM; }
;     else if ((r -= 1024) < 256) { int g = r >> 6; r &= 63; src = p->w_pool + (size_t)g * 512 * 512; dst = (u16*)(ws + OFF_WPOOL) + (size_t)g * 512 * 512; N = 512; Np = 512; K = 512; }
;     else if ((r -= 256) < 8192) { int l = r >> 12; r &= 4095; src = p->w_up + (size_t)l * DM * DFF; gain = p->norm_mlp + l * DM; dst = (u16*)(ws + OFF_WUP) + (size_t)l * DM * DFF; N = DFF; Np = DFF; K = DM; }
;     else { r -= 8192; int l = r >> 12; r &= 4095; src = p->w_down + (size_t)l * DM * DFF; dst = (u16*)(ws + OFF_WDN) + (size_t)l * DM * DFF; N = DM; Np = DM; K = DFF; }
;     const int ntl = Np >> 6, kt = r / ntl, nt = r - kt * ntl;
;     int snt = nt;
;     if (id < 2048) {
.LBB0_244:
	s_andn2_b64 vcc, exec, s[4:5]
	s_cbranch_vccnz .LBB0_295
	v_readlane_b32 s2, v250, 11
	v_readlane_b32 s3, v250, 12
	s_andn2_b64 vcc, exec, s[2:3]
	s_cbranch_vccnz .LBB0_280
	s_load_dwordx2 s[40:41], s[50:51], 0x98
	v_lshrrev_b32_e32 v60, 3, v150
	v_and_b32_e32 v61, 7, v150
	v_lshlrev_b32_e32 v62, 4, v61
	v_lshlrev_b32_e32 v61, 5, v61
	v_lshlrev_b32_e32 v40, 2, v60
	v_mul_u32_u24_e32 v44, 0x104, v60
	v_add_u32_e32 v44, v44, v61
	v_lshrrev_b32_e32 v45, 2, v61
	v_mul_u32_u24_e32 v45, 0x104, v45
	v_add_u32_e32 v45, v45, v40
	s_mov_b32 s1, s78
	s_mov_b32 s2, 0
	s_waitcnt lgkmcnt(0)
	s_min_u32 s4, s1, 0x4e3f
	s_mov_b32 s3, 0
	s_branch .Lpp_entry
.Lpp_ret0:
	v_mov_b32_e32 v41, s10
	v_mad_u32_u24 v41, v60, v41, v61
	global_load_dwordx4 v[0:3], v41, s[8:9]
	global_load_dwordx4 v[4:7], v41, s[8:9] offset:16
	global_load_dword v8, v40, s[28:29]
	s_add_i32 s1, s1, s79
	s_mov_b32 s16, s30
	s_mov_b32 s17, s31
	s_mov_b32 s18, s36
	s_mov_b32 s19, s11
	s_min_u32 s4, s1, 0x4e3f
	s_mov_b32 s3, 1
	s_branch .Lpp_entry
.Lpp_ret1:
	v_mov_b32_e32 v42, s10
	v_mad_u32_u24 v42, v60, v42, v61
	global_load_dwordx4 v[12:15], v42, s[8:9]
	global_load_dwordx4 v[16:19], v42, s[8:9] offset:16
	global_load_dword v20, v40, s[28:29]
	s_add_i32 s1, s1, s79
	s_mov_b32 s20, s30
	s_mov_b32 s21, s31
	s_mov_b32 s22, s36
	s_mov_b32 s23, s11
	s_min_u32 s4, s1, 0x4e3f
	s_mov_b32 s3, 2
	s_branch .Lpp_entry
.Lpp_ret2:
	v_mov_b32_e32 v43, s10
	v_mad_u32_u24 v43, v60, v43, v61
	global_load_dwordx4 v[24:27], v43, s[8:9]
	global_load_dwordx4 v[28:31], v43, s[8:9] offset:16
	global_load_dword v32, v40, s[28:29]
	s_add_i32 s1, s1, s79
	s_mov_b32 s24, s30
	s_mov_b32 s25, s31
	s_mov_b32 s26, s36
	s_mov_b32 s27, s11
	global_load_dword v63, v40, s[28:29]
	global_load_dword v63, v40, s[28:29]
	global_load_dword v63, v40, s[28:29]
.Lpp_loop:
	s_mul_i32 s4, s79, 3
	s_sub_i32 s4, s1, s4
	s_cmpk_gt_u32 s4, 0x4e3f
	s_cbranch_scc1 .Lpp_exit
	s_waitcnt vmcnt(9)
	s_cmp_eq_u32 s19, 1
	s_cselect_b32 s4, 1.0, 0
	v_mov_b32_e32 v46, s4
	s_cmp_eq_u32 s19, 2
	s_cselect_b64 vcc, -1, 0
	v_cndmask_b32_e32 v8, v46, v8, vcc
	v_add_u32_e32 v47, s2, v44
	v_pk_mul_f32 v[0:1], v[0:1], v[8:9] op_sel_hi:[1,0]
	v_pk_mul_f32 v[2:3], v[2:3], v[8:9] op_sel_hi:[1,0]
	v_pk_mul_f32 v[4:5], v[4:5], v[8:9] op_sel_hi:[1,0]
	v_pk_mul_f32 v[6:7], v[6:7], v[8:9] op_sel_hi:[1,0]
	ds_write2_b32 v47, v0, v1 offset1:1
	ds_write2_b32 v47, v2, v3 offset0:2 offset1:3
	ds_write2_b32 v47, v4, v5 offset0:4 offset1:5
	ds_write2_b32 v47, v6, v7 offset0:6 offset1:7
	s_waitcnt lgkmcnt(0)
	s_barrier
	v_add_u32_e32 v47, s2, v45
	ds_read2_b32 v[52:53], v47 offset1:65
	ds_read2_b32 v[54:55], v47 offset0:130 offset1:195
	v_add_u32_e32 v47, 0x410, v47
	ds_read2_b32 v[56:57], v47 offset1:65
	ds_read2_b32 v[58:59], v47 offset0:130 offset1:195
	s_xor_b32 s2, s2, 0x4400
	s_min_u32 s4, s1, 0x4e3f
	s_mov_b32 s3, 3
	s_branch .Lpp_entry
.Lpp_ret3:
	v_mov_b32_e32 v41, s10
	v_mad_u32_u24 v41, v60, v41, v61
	global_load_dwordx4 v[0:3], v41, s[8:9]
	global_load_dwordx4 v[4:7], v41, s[8:9] offset:16
	global_load_dword v8, v40, s[28:29]
	s_add_i32 s1, s1, s79
	s_waitcnt lgkmcnt(0)
	v_cvt_pk_bf16_f32 v48, v52, v53
	v_cvt_pk_bf16_f32 v49, v54, v55
	v_cvt_pk_bf16_f32 v50, v56, v57
	v_cvt_pk_bf16_f32 v51, v58, v59
	v_mov_b32_e32 v46, s18
	v_mad_u32_u24 v46, v60, v46, v62
	global_store_dwordx4 v46, v[48:51], s[16:17]
	s_mov_b32 s16, s30
	s_mov_b32 s17, s31
	s_mov_b32 s18, s36
	s_mov_b32 s19, s11
	s_mul_i32 s4, s79, 3
	s_sub_i32 s4, s1, s4
	s_cmpk_gt_u32 s4, 0x4e3f
	s_cbranch_scc1 .Lpp_exit
	s_waitcnt vmcnt(9)
	s_cmp_eq_u32 s23, 1
	s_cselect_b32 s4, 1.0, 0
	v_mov_b32_e32 v46, s4
	s_cmp_eq_u32 s23, 2
	s_cselect_b64 vcc, -1, 0
	v_cndmask_b32_e32 v20, v46, v20, vcc
	v_add_u32_e32 v47, s2, v44
	v_pk_mul_f32 v[12:13], v[12:13], v[20:21] op_sel_hi:[1,0]
	v_pk_mul_f32 v[14:15], v[14:15], v[20:21] op_sel_hi:[1,0]
	v_pk_mul_f32 v[16:17], v[16:17], v[20:21] op_sel_hi:[1,0]
	v_pk_mul_f32 v[18:19], v[18:19], v[20:21] op_sel_hi:[1,0]
	ds_write2_b32 v47, v12, v13 offset1:1
	ds_write2_b32 v47, v14, v15 offset0:2 offset1:3
	ds_write2_b32 v47, v16, v17 offset0:4 offset1:5
	ds_write2_b32 v47, v18, v19 offset0:6 offset1:7
	s_waitcnt lgkmcnt(0)
	s_barrier
	v_add_u32_e32 v47, s2, v45
	ds_read2_b32 v[52:53], v47 offset1:65
	ds_read2_b32 v[54:55], v47 offset0:130 offset1:195
	v_add_u32_e32 v47, 0x410, v47
	ds_read2_b32 v[56:57], v47 offset1:65
	ds_read2_b32 v[58:59], v47 offset0:130 offset1:195
	s_xor_b32 s2, s2, 0x4400
	s_min_u32 s4, s1, 0x4e3f
	s_mov_b32 s3, 4
	s_branch .Lpp_entry
.Lpp_ret4:
	v_mov_b32_e32 v42, s10
	v_mad_u32_u24 v42, v60, v42, v61
	global_load_dwordx4 v[12:15], v42, s[8:9]
	global_load_dwordx4 v[16:19], v42, s[8:9] offset:16
	global_load_dword v20, v40, s[28:29]
	s_add_i32 s1, s1, s79
	s_waitcnt lgkmcnt(0)
	v_cvt_pk_bf16_f32 v48, v52, v53
	v_cvt_pk_bf16_f32 v49, v54, v55
	v_cvt_pk_bf16_f32 v50, v56, v57
	v_cvt_pk_bf16_f32 v51, v58, v59
	v_mov_b32_e32 v46, s22
	v_mad_u32_u24 v46, v60, v46, v62
	global_store_dwordx4 v46, v[48:51], s[20:21]
	s_mov_b32 s20, s30
	s_mov_b32 s21, s31
	s_mov_b32 s22, s36
	s_mov_b32 s23, s11
	s_mul_i32 s4, s79, 3
	s_sub_i32 s4, s1, s4
	s_cmpk_gt_u32 s4, 0x4e3f
	s_cbranch_scc1 .Lpp_exit
	s_waitcnt vmcnt(9)
	s_cmp_eq_u32 s27, 1
	s_cselect_b32 s4, 1.0, 0
	v_mov_b32_e32 v46, s4
	s_cmp_eq_u32 s27, 2
	s_cselect_b64 vcc, -1, 0
	v_cndmask_b32_e32 v32, v46, v32, vcc
	v_add_u32_e32 v47, s2, v44
	v_pk_mul_f32 v[24:25], v[24:25], v[32:33] op_sel_hi:[1,0]
	v_pk_mul_f32 v[26:27], v[26:27], v[32:33] op_sel_hi:[1,0]
	v_pk_mul_f32 v[28:29], v[28:29], v[32:33] op_sel_hi:[1,0]
	v_pk_mul_f32 v[30:31], v[30:31], v[32:33] op_sel_hi:[1,0]
	ds_write2_b32 v47, v24, v25 offset1:1
	ds_write2_b32 v47, v26, v27 offset0:2 offset1:3
	ds_write2_b32 v47, v28, v29 offset0:4 offset1:5
	ds_write2_b32 v47, v30, v31 offset0:6 offset1:7
	s_waitcnt lgkmcnt(0)
	s_barrier
	v_add_u32_e32 v47, s2, v45
	ds_read2_b32 v[52:53], v47 offset1:65
	ds_read2_b32 v[54:55], v47 offset0:130 offset1:195
	v_add_u32_e32 v47, 0x410, v47
	ds_read2_b32 v[56:57], v47 offset1:65
	ds_read2_b32 v[58:59], v47 offset0:130 offset1:195
	s_xor_b32 s2, s2, 0x4400
	s_min_u32 s4, s1, 0x4e3f
	s_mov_b32 s3, 5
	s_branch .Lpp_entry
; __device__ __forceinline__ void phase_prep(const int tid_, CP p, float* lds) {
;     ...
;   for (int id = blockIdx.x; id < 20032; id += gridDim.x) {
;     int r = id; const float* src; const float* gain = nullptr; u16* dst; int N, Np, K;
;     if (r < 2048) { src = p->w_in0; gain = p->norm_mix0; dst = (u16*)(ws + OFF_WIN); N = NIN; Np = NINP; K = DM; }
;     else if ((r -= 2048) < 192) { src = p->w_qb; gain = p->q_a_norm; dst = (u16*)(ws + OFF_WQB); N = NQ; Np = NQ; K = QR; }
;     else if ((r -= 192) < 128) { src = p->w_kvb; gain = p->kv_a_norm; dst = (u16*)(ws + OFF_WKVB); N = NKV; Np = NKV; K = KVR; }
;     else if ((r -= 128) < 1024) { src = p->w_o0; dst = (u16*)(ws + OFF_WO); N = DM; Np = DM; K = DM; }
;     else if ((r -= 1024) < 256) { int g = r >> 6; r &= 63; src = p->w_pool + (size_t)g * 512 * 512; dst = (u16*)(ws + OFF_WPOOL) + (size_t)g * 512 * 512; N = 512; Np = 512; K = 512; }
;     else if ((r -= 256) < 8192) { int l = r >> 12; r &= 4095; src = p->w_up + (size_t)l * DM * DFF; gain = p->norm_mlp + l * DM; dst = (u16*)(ws + OFF_WUP) + (size_t)l * DM * DFF; N = DFF; Np = DFF; K = DM; }
;     else { r -= 8192; int l = r >> 12; r &= 4095; src = p->w_down + (size_t)l * DM * DFF; dst = (u16*)(ws + OFF_WDN) + (size_t)l * DM * DFF; N = DM; Np = DM; K = DFF; }
;     const int ntl = Np >> 6, kt = r / ntl, nt = r - kt * ntl;
;     int snt = nt;
;     if (id < 2048) {
;       const int j = nt >> 2, q = nt & 3;
;       if (j < 8) snt = (q < 2 ? 16 : 32) + j * 2 + (q & 1);
;       else if (j < 12) snt = (j - 8) * 4 + q;
;     }
;     transpose_tile(tid_, src, gain, N, K, dst, kt, nt, snt, lds);
;   }
;   if (blockIdx.x == 0) { for (int i = tid_; i < 4096; i += 512) ((unsigned*)(ws + OFF_BAR))[i] = 0u; }
;   { float* rss = (float*)(ws + OFF_RSS);
;     for (int idx = blockIdx.x * 512 + tid_; idx < 5 * T; idx += gridDim.x * 512) rss[idx] = 0.f; }
.Lpp_ret5:
	v_mov_b32_e32 v43, s10
	v_mad_u32_u24 v43, v60, v43, v61
	global_load_dwordx4 v[24:27], v43, s[8:9]
	global_load_dwordx4 v[28:31], v43, s[8:9] offset:16
	global_load_dword v32, v40, s[28:29]
	s_add_i32 s1, s1, s79
	s_waitcnt lgkmcnt(0)
	v_cvt_pk_bf16_f32 v48, v52, v53
	v_cvt_pk_bf16_f32 v49, v54, v55
	v_cvt_pk_bf16_f32 v50, v56, v57
	v_cvt_pk_bf16_f32 v51, v58, v59
	v_mov_b32_e32 v46, s26
	v_mad_u32_u24 v46, v60, v46, v62
	global_store_dwordx4 v46, v[48:51], s[24:25]
	s_mov_b32 s24, s30
	s_mov_b32 s25, s31
	s_mov_b32 s26, s36
	s_mov_b32 s27, s11
	s_branch .Lpp_loop
.Lpp_entry:
.Lpp_seg0:
	s_cmpk_lt_u32 s4, 0x800
	s_cbranch_scc1 .Lpp_do0
	s_sub_i32 s4, s4, 0x800
	s_branch .Lpp_seg1
.Lpp_do0:
	s_mov_b32 s42, 0
	s_mov_b32 s43, 0
	s_mov_b32 s37, 0x0
	s_movk_i32 s5, 0x18
	s_movk_i32 s6, 0x10
	s_load_dwordx2 s[8:9], s[50:51], s5
	s_load_dwordx2 s[28:29], s[50:51], s6
	s_mov_b32 s10, 0x3d00
	s_mov_b32 s36, 0x1000
	s_mov_b32 s11, 2
	s_lshr_b32 s5, s4, 6
	s_and_b32 s6, s4, 0x3f
	s_mov_b32 s7, s6
	s_lshr_b32 s4, s6, 2
	s_cmp_lt_u32 s4, 8
	s_cbranch_scc0 .Lpp_in_b
	s_and_b32 s7, s6, 2
	s_lshl_b32 s7, s7, 3
	s_add_i32 s7, s7, 16
	s_lshl_b32 s4, s4, 1
	s_add_i32 s7, s7, s4
	s_and_b32 s4, s6, 1
	s_add_i32 s7, s7, s4
	s_branch .Lpp_in_done
.Lpp_in_b:
	s_cmp_lt_u32 s4, 12
	s_cbranch_scc0 .Lpp_in_done
	s_sub_i32 s7, s6, 32
.Lpp_in_done:
	s_cmp_gt_u32 s7, 60
	s_cselect_b32 s11, 0, s11
	s_cselect_b32 s7, 0, s7
	s_branch .Lpp_common
.Lpp_seg1:
	s_cmpk_lt_u32 s4, 0xc0
	s_cbranch_scc1 .Lpp_do1
	s_sub_i32 s4, s4, 0xc0
	s_branch .Lpp_seg2
.Lpp_do1:
	s_mov_b32 s42, 0
	s_mov_b32 s43, 0
	s_mov_b32 s37, 0x1000000
	s_movk_i32 s5, 0x30
	s_movk_i32 s6, 0x28
	s_load_dwordx2 s[8:9], s[50:51], s5
	s_load_dwordx2 s[28:29], s[50:51], s6
	s_mov_b32 s10, 0x1800
	s_mov_b32 s36, 0x400
	s_mov_b32 s11, 2
	s_mul_i32 s5, s4, 0xaab
	s_lshr_b32 s5, s5, 16
	s_mul_i32 s6, s5, 24
	s_sub_i32 s6, s4, s6
	s_mov_b32 s7, s6
	s_branch .Lpp_common
.Lpp_seg2:
	s_cmpk_lt_u32 s4, 0x80
	s_cbranch_scc1 .Lpp_do2
	s_sub_i32 s4, s4, 0x80
	s_branch .Lpp_seg3
.Lpp_do2:
	s_mov_b32 s42, 0
	s_mov_b32 s43, 0
	s_mov_b32 s37, 0x1180000
	s_movk_i32 s5, 0x40
	s_movk_i32 s6, 0x38
	s_load_dwordx2 s[8:9], s[50:51], s5
	s_load_dwordx2 s[28:29], s[50:51], s6
	s_mov_b32 s10, 0x2000
	s_mov_b32 s36, 0x200
	s_mov_b32 s11, 2
	s_lshr_b32 s5, s4, 5
	s_and_b32 s6, s4, 0x1f
	s_mov_b32 s7, s6
	s_branch .Lpp_common
.Lpp_seg3:
	s_cmpk_lt_u32 s4, 0x400
	s_cbranch_scc1 .Lpp_do3
	s_sub_i32 s4, s4, 0x400
	s_branch .Lpp_seg4
.Lpp_do3:
	s_mov_b32 s42, 0
	s_mov_b32 s43, 0
	s_mov_b32 s37, 0x1280000
	s_movk_i32 s5, 0x58
	s_movk_i32 s6, 0x10
	s_load_dwordx2 s[8:9], s[50:51], s5
	s_load_dwordx2 s[28:29], s[50:51], s6
	s_mov_b32 s10, 0x2000
	s_mov_b32 s36, 0x1000
	s_mov_b32 s11, 1
	s_lshr_b32 s5, s4, 5
	s_and_b32 s6, s4, 0x1f
	s_mov_b32 s7, s6
	s_branch .Lpp_common
.Lpp_seg4:
	s_cmpk_lt_u32 s4, 0x100
	s_cbranch_scc1 .Lpp_do4
	s_sub_i32 s4, s4, 0x100
	s_branch .Lpp_seg5
.Lpp_do4:
	s_mov_b32 s42, 0
	s_mov_b32 s43, 0
	s_mov_b32 s37, 0x1a80000
	s_lshr_b32 s5, s4, 6
	s_and_b32 s4, s4, 63
	s_lshl_b32 s42, s5, 20
	s_lshl_b32 s5, s5, 19
	s_add_u32 s37, s37, s5
	s_movk_i32 s5, 0x68
	s_movk_i32 s6, 0x10
	s_load_dwordx2 s[8:9], s[50:51], s5
	s_load_dwordx2 s[28:29], s[50:51], s6
	s_mov_b32 s10, 0x800
	s_mov_b32 s36, 0x400
	s_mov_b32 s11, 1
	s_lshr_b32 s5, s4, 3
	s_and_b32 s6, s4, 0x7
	s_mov_b32 s7, s6
	s_branch .Lpp_common
.Lpp_seg5:
	s_cmpk_lt_u32 s4, 0x2000
	s_cbranch_scc1 .Lpp_do5
	s_sub_i32 s4, s4, 0x2000
	s_branch .Lpp_seg6
.Lpp_do5:
	s_mov_b32 s42, 0
	s_mov_b32 s43, 0
	s_mov_b32 s37, 0x1c80000
	s_lshr_b32 s5, s4, 12
	s_and_b32 s4, s4, 0xfff
	s_lshl_b32 s42, s5, 26
	s_lshl_b32 s43, s5, 13
	s_lshl_b32 s5, s5, 25
	s_add_u32 s37, s37, s5
	s_movk_i32 s5, 0x80
	s_movk_i32 s6, 0x78
	s_load_dwordx2 s[8:9], s[50:51], s5
	s_load_dwordx2 s[28:29], s[50:51], s6
	s_mov_b32 s10, 0x8000
	s_mov_b32 s36, 0x1000
	s_mov_b32 s11, 2
	s_lshr_b32 s5, s4, 7
	s_and_b32 s6, s4, 0x7f
	s_mov_b32 s7, s6
	s_branch .Lpp_common
.Lpp_seg6:
	s_mov_b32 s42, 0
	s_mov_b32 s43, 0
	s_mov_b32 s37, 0x5c80000
	s_lshr_b32 s5, s4, 12
	s_and_b32 s4, s4, 0xfff
	s_lshl_b32 s42, s5, 26
	s_lshl_b32 s5, s5, 25
	s_add_u32 s37, s37, s5
	s_movk_i32 s5, 0x88
	s_movk_i32 s6, 0x10
	s_load_dwordx2 s[8:9], s[50:51], s5
	s_load_dwordx2 s[28:29], s[50:51], s6
	s_mov_b32 s10, 0x2000
	s_mov_b32 s36, 0x4000
	s_mov_b32 s11, 1
	s_lshr_b32 s5, s4, 5
	s_and_b32 s6, s4, 0x1f
	s_mov_b32 s7, s6
	s_branch .Lpp_common
.Lpp_common:
	s_lshl_b32 s4, s5, 6
	s_mul_i32 s4, s4, s10
	s_lshl_b32 s7, s7, 8
	s_add_u32 s4, s4, s7
	s_add_u32 s4, s4, s42
	s_lshl_b32 s7, s5, 8
	s_cmp_eq_u32 s11, 2
	s_cselect_b32 s7, s7, 0
	s_add_u32 s7, s7, s43
	s_lshl_b32 s6, s6, 6
	s_mul_i32 s6, s6, s36
	s_lshl_b32 s5, s5, 7
	s_add_u32 s6, s6, s5
	s_add_u32 s6, s6, s37
	s_add_u32 s30, s40, s6
	s_addc_u32 s31, s41, 0
	s_waitcnt lgkmcnt(0)
	s_add_u32 s8, s8, s4
	s_addc_u32 s9, s9, 0
	s_add_u32 s28, s28, s7
	s_addc_u32 s29, s29, 0
	s_cmp_eq_u32 s3, 0
	s_cbranch_scc1 .Lpp_ret0
	s_cmp_eq_u32 s3, 1
	s_cbranch_scc1 .Lpp_ret1
	s_cmp_eq_u32 s3, 2
	s_cbranch_scc1 .Lpp_ret2
	s_cmp_eq_u32 s3, 3
	s_cbranch_scc1 .Lpp_ret3
	s_cmp_eq_u32 s3, 4
	s_cbranch_scc1 .Lpp_ret4
	s_cmp_eq_u32 s3, 5
	s_cbranch_scc1 .Lpp_ret5
	s_branch .Lpp_exit
.Lpp_exit:
	s_waitcnt vmcnt(0)
.LBB0_280:
	s_movk_i32 s1, 0x1000
	v_readlane_b32 s2, v250, 13
	v_cmp_gt_i32_e32 vcc, s1, v150
	v_readlane_b32 s3, v250, 14
	s_and_b64 s[2:3], s[2:3], vcc
	s_and_saveexec_b64 s[4:5], s[2:3]
	v_readlane_b32 s16, v250, 31
	s_cbranch_execz .LBB0_288
	s_load_dwordx4 s[8:11], s[50:51], 0x90
	v_max_i32_e32 v0, 0xe00, v150
	v_sub_u32_e32 v0, v0, v150
	v_add_u32_e32 v1, 0x1ff, v0
	s_movk_i32 s1, 0x1ff
	s_waitcnt lgkmcnt(0)
	s_mov_b64 s[2:3], s[10:11]
	s_add_u32 s6, s2, 0x9f70000
	s_addc_u32 s7, s3, 0
	v_cmp_lt_u32_e32 vcc, s1, v1
	s_mov_b64 s[10:11], -1
	v_mov_b32_e32 v0, v150
	s_and_saveexec_b64 s[8:9], vcc
	s_cbranch_execz .LBB0_285
	v_lshrrev_b32_e32 v0, 9, v1
	v_add_u32_e32 v2, 1, v0
	v_and_b32_e32 v3, 0xfffffe, v2
	v_add_u32_e32 v151, 0x200, v150
	s_mov_b64 s[10:11], 0
	v_mov_b32_e32 v4, v3
	v_mov_b64_e32 v[0:1], v[150:151]
